# GLA output units (gla_o) moved from the all-workgroup part of phase 7 into the 224 workgroups that otherwise wait for the rwkv_apply workgroups (own counter barrier before their weight conversion + GE
# baseline (speedup 1.0000x reference)
.LBB0_874:
	v_writelane_b32 v241, s38, 30
	v_writelane_b32 v241, s39, 31
	s_waitcnt vmcnt(0)
	s_barrier
	s_mov_b64 s[0:1], exec
	v_readlane_b32 s4, v240, 9
	v_readlane_b32 s5, v240, 10
	s_and_b64 s[4:5], s[0:1], s[4:5]
	s_mov_b64 exec, s[4:5]
	s_cbranch_execz .LBB0_926
	s_add_i32 s3, 0, 0x23fc0
	v_mov_b32_e32 v0, s3
	s_waitcnt vmcnt(0) expcnt(0) lgkmcnt(0)
	ds_read_b32 v2, v0
	s_add_i32 s3, 0, 0x23fc4
	v_mov_b32_e32 v0, s3
	ds_read_b32 v0, v0
	s_waitcnt lgkmcnt(1)
	v_cmp_ne_u32_e32 vcc, 0, v2
	s_cbranch_vccnz .LBB0_890
	s_add_u32 s4, s52, 0x40200
	s_addc_u32 s5, s53, 0
	s_add_u32 s6, s52, 0x40400
	s_addc_u32 s7, s53, 0
	s_add_u32 s8, s52, 0x40500
	s_addc_u32 s9, s53, 0
	s_add_u32 s12, s52, 0x40600
	s_addc_u32 s13, s53, 0
	s_add_u32 s14, s52, 0x40700
	s_addc_u32 s15, s53, 0
	s_add_u32 s16, s52, 0x40800
	s_addc_u32 s17, s53, 0
	s_add_u32 s18, s52, 0x40900
	s_addc_u32 s19, s53, 0
	s_add_u32 s20, s52, 0x40a00
	s_addc_u32 s21, s53, 0
	s_add_u32 s22, s52, 0x40b00
	s_addc_u32 s23, s53, 0
	s_add_u32 s26, s52, 0x40c00
	s_addc_u32 s27, s53, 0
	s_add_u32 s36, s52, 0x40d00
	s_addc_u32 s37, s53, 0
	s_add_u32 s38, s52, 0x40e00
	s_addc_u32 s39, s53, 0
	s_add_u32 s42, s52, 0x40f00
	s_addc_u32 s43, s53, 0
	s_add_u32 s46, s52, 0x41000
	s_addc_u32 s47, s53, 0
	s_add_u32 s48, s52, 0x41100
	s_addc_u32 s49, s53, 0
	s_add_u32 s10, s52, 0x41200
	v_readlane_b32 s3, v240, 0
	s_addc_u32 s11, s53, 0
	s_mul_i32 s3, s31, s3
	s_add_u32 s28, s52, 0x41300
	s_mul_i32 s3, s3, s30
	s_addc_u32 s29, s53, 0
	s_mov_b32 s35, 1
	v_mov_b32_e32 v16, 0
	s_branch .LBB0_878

.LBB0_990:
	s_and_b64 vcc, exec, s[4:5]
	s_cbranch_vccz .LBB0_1045
	s_mov_b64 s[0:1], -1
	s_and_b64 vcc, exec, s[12:13]
	s_cbranch_vccz .LBB0_1020
	v_readlane_b32 s38, v241, 30
	v_readlane_b32 s39, v241, 31
	s_nop 4
	v_lshrrev_b32_e32 v0, 2, v144
	s_movk_i32 s0, 0x70
	v_lshlrev_b32_e32 v2, 4, v144
	v_and_or_b32 v0, v0, s0, v133
	v_and_b32_e32 v34, 0xf0, v2
	s_add_i32 s0, 0, 0x11000
	v_and_b32_e32 v7, 48, v144
	v_add_u32_e32 v2, s0, v34
	v_add_u32_e32 v8, 0, v7
	v_add_u32_e32 v7, s0, v7
	s_lshl_b32 s0, s57, 7
	s_add_i32 s0, s0, 0
	v_mul_u32_u24_e32 v10, 0x410, v100
	v_lshlrev_b32_e32 v11, 2, v133
	v_add3_u32 v54, s0, v10, v11
	v_mul_u32_u24_e32 v10, 0x410, v147
	s_movk_i32 s1, 0x110
	v_lshl_or_b32 v6, s57, 5, v133
	v_add3_u32 v58, s0, v10, v11
	v_mul_u32_u24_e32 v10, 0x410, v145
	v_lshl_add_u32 v33, v0, 1, 0
	v_lshlrev_b32_e32 v0, 3, v144
	v_mul_lo_u32 v6, v6, s1
	s_lshl_b32 s1, s57, 8
	s_add_i32 s3, 0, 0x15400
	v_add3_u32 v63, s0, v10, v11
	v_mul_u32_u24_e32 v10, 0x410, v132
	v_mov_b32_e32 v35, 0
	s_add_i32 s1, s3, s1
	v_add3_u32 v68, s0, v10, v11
	v_mul_u32_u24_e32 v10, 0x410, v101
	v_lshrrev_b32_e32 v40, 3, v144
	v_and_b32_e32 v0, 56, v0
	v_lshl_add_u64 v[36:37], s[44:45], 0, v[34:35]
	v_add3_u32 v73, s0, v10, v11
	s_add_u32 s6, s52, 0x9000000
	v_mul_u32_u24_e32 v10, 0x410, v40
	v_lshlrev_b32_e32 v34, 2, v0
	v_bfe_u32 v1, v144, 4, 2
	v_lshl_add_u32 v75, v40, 2, s3
	s_addc_u32 s7, s53, 0
	v_add3_u32 v76, 0, v10, v34
	v_add_u32_e32 v10, 0x600, v144
	s_ashr_i32 s3, s2, 31
	v_add_u32_e32 v4, 0x200, v144
	v_lshl_add_u32 v55, v100, 2, s1
	v_lshl_add_u32 v59, v147, 2, s1
	v_lshl_add_u32 v64, v145, 2, s1
	v_lshl_add_u32 v69, v132, 2, s1
	v_lshl_add_u32 v74, v101, 2, s1
	v_lshrrev_b32_e32 v10, 9, v10
	v_lshlrev_b32_e32 v11, 4, v1
	s_sub_i32 s0, s2, 32
	s_mov_b32 s1, 0
	s_lshl_b64 s[0:1], s[0:1], 17
	v_lshrrev_b32_e32 v38, 4, v4
	v_lshl_or_b32 v77, v10, 2, v1
	v_lshl_or_b32 v44, v10, 6, v11
	v_lshlrev_b32_e32 v10, 8, v144
	v_lshlrev_b32_e32 v12, 10, v133
	s_mov_b32 s3, 0x1c000
	s_add_u32 s0, s50, s0
	v_lshrrev_b32_e32 v4, 9, v4
	v_lshrrev_b32_e32 v32, 4, v144
	v_lshl_add_u64 v[42:43], s[38:39], 0, v[34:35]
	v_and_or_b32 v34, v10, s3, v12
	s_addc_u32 s1, s51, s1
	v_lshl_or_b32 v78, v4, 2, v1
	v_lshl_or_b32 v48, v4, 6, v11
	v_lshrrev_b32_e32 v4, 9, v144
	v_mul_u32_u24_e32 v3, 0x110, v32
	v_mul_u32_u24_e32 v5, 0x110, v38
	v_mul_u32_u24_e32 v9, 0x110, v133
	v_lshl_add_u64 v[46:47], s[0:1], 0, v[34:35]
	s_ashr_i32 s1, s30, 31
	s_movk_i32 s0, 0xe0
	v_lshl_or_b32 v79, v4, 2, v1
	v_mov_b32_e32 v1, 0x80
	s_mov_b32 s5, 0
	v_mov_b32_e32 v39, v35
	v_cmp_eq_u32_e32 vcc, 0, v133
	v_add_u32_e32 v56, 0x410, v54
	v_add_u32_e32 v57, 0x820, v54
	v_add_u32_e32 v60, 0x4100, v54
	v_add_u32_e32 v61, 0x4510, v54
	v_add_u32_e32 v62, 0x4920, v54
	v_add_u32_e32 v65, 0x8200, v54
	v_add_u32_e32 v66, 0x8610, v54
	v_add_u32_e32 v67, 0x8a20, v54
	v_add_u32_e32 v70, 0xc300, v54
	v_add_u32_e32 v71, 0xc710, v54
	v_add_u32_e32 v72, 0xcb20, v54
	v_mov_b32_e32 v41, v35
	v_mov_b32_e32 v45, v35
	s_lshl_b64 s[8:9], s[0:1], 17
	v_mov_b32_e32 v49, v35
	v_lshl_or_b32 v50, v79, 4, v1
	v_mov_b32_e32 v51, v35
	v_lshl_or_b32 v52, v4, 6, v11
	v_mov_b32_e32 v53, v35
	s_movk_i32 s3, 0x440
	s_movk_i32 s16, 0x7fff
	s_mov_b64 s[12:13], 0x100
	s_movk_i32 s17, 0x5400
	v_add_u32_e32 v80, v2, v3
	v_add_u32_e32 v81, v2, v5
	v_add_u32_e32 v82, v8, v6
	v_add_u32_e32 v83, v7, v9
	v_mov_b32_e32 v84, 0x358637bd
	s_mov_b32 s18, 0x800000
	v_lshlrev_b32_e32 v34, 1, v0
	s_mov_b64 s[14:15], 0x1000
	s_movk_i32 s19, 0x1000
	s_mov_b32 s20, 0xffff0000
	v_mov_b32_e32 v85, 0x5400
	s_sub_i32 s21, s2, 32
	s_branch .LBB0_840
.LBB0_839:
	s_or_b64 exec, exec, s[10:11]
	v_lshl_add_u64 v[0:1], s[0:1], 0, v[40:41]
	v_mov_b64_e32 v[2:3], s[44:45]
	v_mad_u64_u32 v[2:3], s[0:1], v0, s17, v[2:3]
	v_mov_b32_e32 v4, v3
	v_mad_u64_u32 v[4:5], s[0:1], v1, s17, v[4:5]
	v_mov_b32_e32 v3, v4
	s_lshl_b32 s4, s22, 9
	v_lshl_add_u64 v[2:3], v[2:3], 0, s[4:5]
	v_lshl_add_u64 v[2:3], v[2:3], 0, v[34:35]
	v_add_co_u32_e64 v4, s[0:1], s19, v2
	s_waitcnt lgkmcnt(0)
	s_barrier
	global_load_dwordx4 v[6:9], v[42:43], off offset:16
	global_load_dwordx4 v[10:13], v[42:43], off
	v_addc_co_u32_e64 v5, s[0:1], 0, v3, s[0:1]
	global_load_dwordx4 v[14:17], v[4:5], off
	v_lshlrev_b64 v[0:1], 11, v[0:1]
	v_lshl_add_u64 v[0:1], s[6:7], 0, v[0:1]
	ds_read2st64_b32 v[4:5], v75 offset1:1
	ds_read2st64_b32 v[26:27], v75 offset0:2 offset1:3
	ds_read2st64_b32 v[28:29], v75 offset0:4 offset1:5
	ds_read2st64_b32 v[30:31], v75 offset0:6 offset1:7
	ds_read_b128 v[18:21], v76
	ds_read_b128 v[22:25], v76 offset:16
	v_lshl_add_u64 v[86:87], v[0:1], 0, s[4:5]
	s_waitcnt lgkmcnt(5)
	v_add_f32_e32 v0, 0, v4
	v_add_f32_e32 v0, v0, v5
	s_waitcnt lgkmcnt(4)
	v_add_f32_e32 v0, v0, v26
	v_add_f32_e32 v0, v0, v27
	s_waitcnt lgkmcnt(3)
	v_add_f32_e32 v0, v0, v28
	v_add_f32_e32 v0, v0, v29
	s_waitcnt lgkmcnt(2)
	v_add_f32_e32 v0, v0, v30
	v_add_f32_e32 v0, v0, v31
	v_fmamk_f32 v0, v0, 0x3b800000, v84
	v_mul_f32_e32 v1, 0x4b800000, v0
	v_cmp_gt_f32_e64 s[0:1], s18, v0
	v_lshl_add_u64 v[30:31], v[2:3], 0, s[14:15]
	s_add_i32 s21, s21, 0xe0
	v_cndmask_b32_e64 v0, v0, v1, s[0:1]
	v_rsq_f32_e32 v4, v0
	global_load_dwordx4 v[26:29], v[30:31], off offset:128
	global_load_dwordx4 v[0:3], v[30:31], off offset:384
	s_cmpk_gt_i32 s21, 0x1ff
	v_lshl_add_u64 v[46:47], v[46:47], 0, s[8:9]
	v_mul_f32_e32 v5, 0x45800000, v4
	v_cndmask_b32_e64 v4, v4, v5, s[0:1]
	s_waitcnt vmcnt(4) lgkmcnt(0)
	v_pk_mul_f32 v[8:9], v[24:25], v[8:9]
	s_waitcnt vmcnt(3)
	v_pk_mul_f32 v[12:13], v[20:21], v[12:13]
	v_pk_mul_f32 v[10:11], v[18:19], v[10:11]
	v_pk_mul_f32 v[6:7], v[22:23], v[6:7]
	v_mov_b32_e32 v18, v10
	v_mov_b32_e32 v19, v12
	v_mov_b32_e32 v12, v11
	v_mov_b32_e32 v10, v6
	v_mov_b32_e32 v11, v8
	v_mov_b32_e32 v8, v7
	s_waitcnt vmcnt(2)
	v_lshlrev_b32_e32 v7, 16, v15
	v_lshlrev_b32_e32 v6, 16, v14
	v_and_b32_e32 v15, 0xffff0000, v15
	v_and_b32_e32 v14, 0xffff0000, v14
	v_lshlrev_b32_e32 v20, 16, v16
	v_mul_f32_e32 v5, 0xbfb8aa3b, v6
	v_mul_f32_e32 v22, 0xbfb8aa3b, v14
	v_mul_f32_e32 v23, 0xbfb8aa3b, v7
	v_mul_f32_e32 v24, 0xbfb8aa3b, v15
	v_mul_f32_e32 v25, 0xbfb8aa3b, v20
	v_exp_f32_e32 v5, v5
	v_exp_f32_e32 v22, v22
	v_exp_f32_e32 v23, v23
	v_exp_f32_e32 v24, v24
	v_exp_f32_e32 v25, v25
	v_lshlrev_b32_e32 v21, 16, v17
	v_and_b32_e32 v17, 0xffff0000, v17
	v_and_b32_e32 v16, 0xffff0000, v16
	v_mul_f32_e32 v89, 0xbfb8aa3b, v21
	v_mul_f32_e32 v90, 0xbfb8aa3b, v17
	v_mul_f32_e32 v88, 0xbfb8aa3b, v16
	v_exp_f32_e32 v89, v89
	v_exp_f32_e32 v91, v90
	v_add_f32_e32 v5, 1.0, v5
	v_add_f32_e32 v90, 1.0, v22
	v_add_f32_e32 v23, 1.0, v23
	v_add_f32_e32 v92, 1.0, v24
	v_exp_f32_e32 v88, v88
	v_add_f32_e32 v93, 1.0, v25
	v_rcp_f32_e32 v22, v5
	v_rcp_f32_e32 v24, v90
	v_rcp_f32_e32 v23, v23
	v_rcp_f32_e32 v25, v92
	v_add_f32_e32 v89, 1.0, v89
	v_add_f32_e32 v94, 1.0, v88
	v_rcp_f32_e32 v88, v93
	v_rcp_f32_e32 v89, v89
	v_pk_mul_f32 v[6:7], v[22:23], v[6:7]
	v_pk_mul_f32 v[14:15], v[24:25], v[14:15]
	v_pk_mul_f32 v[6:7], v[4:5], v[6:7] op_sel_hi:[0,1]
	v_pk_mul_f32 v[14:15], v[4:5], v[14:15] op_sel_hi:[0,1]
	v_add_f32_e32 v5, 1.0, v91
	v_rcp_f32_e32 v90, v94
	v_rcp_f32_e32 v91, v5
	v_pk_mul_f32 v[12:13], v[12:13], v[14:15]
	v_pk_mul_f32 v[14:15], v[88:89], v[20:21]
	v_pk_mul_f32 v[6:7], v[18:19], v[6:7]
	v_pk_mul_f32 v[14:15], v[4:5], v[14:15] op_sel_hi:[0,1]
	v_pk_mul_f32 v[10:11], v[10:11], v[14:15]
	v_pk_mul_f32 v[14:15], v[90:91], v[16:17]
	v_bfe_u32 v16, v12, 16, 1
	v_pk_mul_f32 v[14:15], v[4:5], v[14:15] op_sel_hi:[0,1]
	v_pk_mul_f32 v[8:9], v[8:9], v[14:15]
	v_bfe_u32 v15, v13, 16, 1
	v_bfe_u32 v5, v9, 16, 1
	v_bfe_u32 v14, v8, 16, 1
	v_add3_u32 v12, v12, v16, s16
	v_add3_u32 v13, v13, v15, s16
	v_add3_u32 v8, v8, v14, s16
	v_add3_u32 v5, v9, v5, s16
	v_bfe_u32 v9, v6, 16, 1
	v_bfe_u32 v14, v7, 16, 1
	v_bfe_u32 v15, v10, 16, 1
	v_bfe_u32 v16, v11, 16, 1
	v_add3_u32 v11, v11, v16, s16
	v_add3_u32 v10, v10, v15, s16
	v_add3_u32 v7, v7, v14, s16
	v_add3_u32 v6, v6, v9, s16
	v_lshrrev_b32_e32 v6, 16, v6
	v_lshrrev_b32_e32 v7, 16, v7
	v_lshrrev_b32_e32 v9, 16, v10
	v_lshrrev_b32_e32 v10, 16, v11
	v_and_or_b32 v11, v5, s20, v10
	v_and_or_b32 v10, v8, s20, v9
	v_and_or_b32 v9, v13, s20, v7
	v_and_or_b32 v8, v12, s20, v6
	v_lshl_add_u64 v[6:7], v[86:87], 0, v[34:35]
	global_store_dwordx4 v[6:7], v[8:11], off
	global_load_dwordx4 v[8:11], v[42:43], off offset:256
	s_nop 0
	global_load_dwordx4 v[12:15], v[42:43], off offset:272
	s_waitcnt vmcnt(4)
	v_lshlrev_b32_e32 v25, 16, v27
	v_lshlrev_b32_e32 v24, 16, v26
	v_and_b32_e32 v26, 0xffff0000, v26
	v_mul_f32_e32 v5, 0xbfb8aa3b, v24
	v_mul_f32_e32 v91, 0xbfb8aa3b, v25
	v_mul_f32_e32 v90, 0xbfb8aa3b, v26
	v_exp_f32_e32 v5, v5
	v_exp_f32_e32 v91, v91
	v_exp_f32_e32 v90, v90
	ds_read_b128 v[16:19], v76 offset:256
	ds_read_b128 v[20:23], v76 offset:272
	global_load_dwordx4 v[86:89], v[30:31], off offset:256
	v_lshlrev_b32_e32 v30, 16, v28
	v_and_b32_e32 v28, 0xffff0000, v28
	v_and_b32_e32 v27, 0xffff0000, v27
	v_mul_f32_e32 v94, 0xbfb8aa3b, v28
	v_add_f32_e32 v5, 1.0, v5
	v_add_f32_e32 v91, 1.0, v91
	v_mul_f32_e32 v92, 0xbfb8aa3b, v27
	v_exp_f32_e32 v94, v94
	v_add_f32_e32 v96, 1.0, v90
	v_rcp_f32_e32 v90, v5
	v_rcp_f32_e32 v91, v91
	v_mul_f32_e32 v93, 0xbfb8aa3b, v30
	v_exp_f32_e32 v92, v92
	v_exp_f32_e32 v93, v93
	v_lshlrev_b32_e32 v31, 16, v29
	v_add_f32_e32 v5, 1.0, v94
	v_pk_mul_f32 v[24:25], v[90:91], v[24:25]
	v_and_b32_e32 v29, 0xffff0000, v29
	v_mul_f32_e32 v95, 0xbfb8aa3b, v31
	v_add_f32_e32 v97, 1.0, v92
	v_pk_mul_f32 v[24:25], v[4:5], v[24:25] op_sel_hi:[0,1]
	v_exp_f32_e32 v95, v95
	v_add_f32_e32 v98, 1.0, v93
	v_rcp_f32_e32 v92, v96
	v_rcp_f32_e32 v93, v97
	v_rcp_f32_e32 v94, v98
	v_pk_mul_f32 v[26:27], v[92:93], v[26:27]
	s_nop 0
	v_pk_mul_f32 v[26:27], v[4:5], v[26:27] op_sel_hi:[0,1]
	s_waitcnt vmcnt(2) lgkmcnt(1)
	v_pk_mul_f32 v[10:11], v[18:19], v[10:11]
	v_pk_mul_f32 v[8:9], v[16:17], v[8:9]
	s_waitcnt vmcnt(1) lgkmcnt(0)
	v_pk_mul_f32 v[14:15], v[22:23], v[14:15]
	v_pk_mul_f32 v[12:13], v[20:21], v[12:13]
	v_mov_b32_e32 v16, v8
	v_mov_b32_e32 v17, v10
	v_mov_b32_e32 v10, v9
	v_mov_b32_e32 v8, v12
	v_mov_b32_e32 v9, v14
	v_mov_b32_e32 v14, v13
	v_pk_mul_f32 v[12:13], v[24:25], v[16:17]
	v_mul_f32_e32 v16, 0xbfb8aa3b, v29
	v_exp_f32_e32 v17, v16
	v_add_f32_e32 v16, 1.0, v95
	v_rcp_f32_e32 v95, v16
	v_rcp_f32_e32 v16, v5
	v_add_f32_e32 v5, 1.0, v17
	v_rcp_f32_e32 v17, v5
	v_pk_mul_f32 v[18:19], v[94:95], v[30:31]
	v_pk_mul_f32 v[10:11], v[26:27], v[10:11]
	v_pk_mul_f32 v[18:19], v[4:5], v[18:19] op_sel_hi:[0,1]
	v_pk_mul_f32 v[16:17], v[16:17], v[28:29]
	v_pk_mul_f32 v[8:9], v[18:19], v[8:9]
	v_pk_mul_f32 v[16:17], v[4:5], v[16:17] op_sel_hi:[0,1]
	v_pk_mul_f32 v[14:15], v[16:17], v[14:15]
	v_bfe_u32 v17, v11, 16, 1
	v_bfe_u32 v5, v15, 16, 1
	v_bfe_u32 v16, v14, 16, 1
	v_bfe_u32 v18, v10, 16, 1
	v_add3_u32 v18, v10, v18, s16
	v_add3_u32 v17, v11, v17, s16
	v_add3_u32 v10, v14, v16, s16
	v_add3_u32 v5, v15, v5, s16
	v_bfe_u32 v11, v12, 16, 1
	v_bfe_u32 v14, v13, 16, 1
	v_bfe_u32 v15, v8, 16, 1
	v_bfe_u32 v16, v9, 16, 1
	v_add3_u32 v9, v9, v16, s16
	v_add3_u32 v8, v8, v15, s16
	v_add3_u32 v13, v13, v14, s16
	v_add3_u32 v11, v12, v11, s16
	v_lshrrev_b32_e32 v12, 16, v11
	v_lshrrev_b32_e32 v13, 16, v13
	v_lshrrev_b32_e32 v8, 16, v8
	v_lshrrev_b32_e32 v9, 16, v9
	v_and_or_b32 v11, v5, s20, v9
	v_and_or_b32 v10, v10, s20, v8
	v_and_or_b32 v9, v17, s20, v13
	v_and_or_b32 v8, v18, s20, v12
	global_store_dwordx4 v[6:7], v[8:11], off offset:128
	global_load_dwordx4 v[8:11], v[42:43], off offset:512
	s_nop 0
	global_load_dwordx4 v[12:15], v[42:43], off offset:528
	s_waitcnt vmcnt(3)
	v_lshlrev_b32_e32 v25, 16, v87
	v_lshlrev_b32_e32 v24, 16, v86
	v_and_b32_e32 v27, 0xffff0000, v87
	v_and_b32_e32 v26, 0xffff0000, v86
	v_lshlrev_b32_e32 v28, 16, v88
	v_and_b32_e32 v30, 0xffff0000, v88
	v_mul_f32_e32 v5, 0xbfb8aa3b, v24
	v_mul_f32_e32 v86, 0xbfb8aa3b, v26
	v_mul_f32_e32 v87, 0xbfb8aa3b, v25
	v_mul_f32_e32 v88, 0xbfb8aa3b, v27
	v_exp_f32_e32 v5, v5
	v_exp_f32_e32 v86, v86
	v_exp_f32_e32 v87, v87
	v_exp_f32_e32 v88, v88
	v_lshlrev_b32_e32 v29, 16, v89
	v_and_b32_e32 v31, 0xffff0000, v89
	v_mul_f32_e32 v89, 0xbfb8aa3b, v28
	v_mul_f32_e32 v90, 0xbfb8aa3b, v30
	v_exp_f32_e32 v91, v89
	v_exp_f32_e32 v92, v90
	v_add_f32_e32 v5, 1.0, v5
	v_add_f32_e32 v89, 1.0, v86
	v_add_f32_e32 v87, 1.0, v87
	v_add_f32_e32 v90, 1.0, v88
	ds_read_b128 v[16:19], v76 offset:512
	ds_read_b128 v[20:23], v76 offset:528
	v_rcp_f32_e32 v86, v5
	v_rcp_f32_e32 v88, v89
	v_rcp_f32_e32 v87, v87
	v_rcp_f32_e32 v89, v90
	v_add_f32_e32 v5, 1.0, v91
	v_rcp_f32_e32 v90, v5
	v_pk_mul_f32 v[24:25], v[86:87], v[24:25]
	v_pk_mul_f32 v[26:27], v[88:89], v[26:27]
	v_pk_mul_f32 v[24:25], v[4:5], v[24:25] op_sel_hi:[0,1]
	v_pk_mul_f32 v[26:27], v[4:5], v[26:27] op_sel_hi:[0,1]
	v_mul_f32_e32 v5, 0xbfb8aa3b, v29
	v_exp_f32_e32 v5, v5
	s_waitcnt vmcnt(1) lgkmcnt(1)
	v_pk_mul_f32 v[10:11], v[18:19], v[10:11]
	v_pk_mul_f32 v[8:9], v[16:17], v[8:9]
	s_waitcnt vmcnt(0) lgkmcnt(0)
	v_pk_mul_f32 v[14:15], v[22:23], v[14:15]
	v_pk_mul_f32 v[12:13], v[20:21], v[12:13]
	v_mov_b32_e32 v16, v8
	v_mov_b32_e32 v17, v10
	v_mov_b32_e32 v10, v9
	v_mov_b32_e32 v8, v12
	v_mov_b32_e32 v9, v14
	v_mov_b32_e32 v14, v13
	v_pk_mul_f32 v[12:13], v[24:25], v[16:17]
	v_mul_f32_e32 v17, 0xbfb8aa3b, v31
	v_exp_f32_e32 v17, v17
	v_add_f32_e32 v5, 1.0, v5
	v_add_f32_e32 v16, 1.0, v92
	v_rcp_f32_e32 v91, v5
	v_add_f32_e32 v5, 1.0, v17
	v_rcp_f32_e32 v16, v16
	v_rcp_f32_e32 v17, v5
	v_pk_mul_f32 v[18:19], v[90:91], v[28:29]
	v_pk_mul_f32 v[10:11], v[26:27], v[10:11]
	v_pk_mul_f32 v[18:19], v[4:5], v[18:19] op_sel_hi:[0,1]
	v_pk_mul_f32 v[16:17], v[16:17], v[30:31]
	v_pk_mul_f32 v[8:9], v[18:19], v[8:9]
	v_pk_mul_f32 v[16:17], v[4:5], v[16:17] op_sel_hi:[0,1]
	v_pk_mul_f32 v[14:15], v[16:17], v[14:15]
	v_bfe_u32 v17, v11, 16, 1
	v_bfe_u32 v5, v15, 16, 1
	v_bfe_u32 v16, v14, 16, 1
	v_bfe_u32 v18, v10, 16, 1
	v_add3_u32 v18, v10, v18, s16
	v_add3_u32 v17, v11, v17, s16
	v_add3_u32 v10, v14, v16, s16
	v_add3_u32 v5, v15, v5, s16
	v_bfe_u32 v11, v12, 16, 1
	v_bfe_u32 v14, v13, 16, 1
	v_bfe_u32 v15, v8, 16, 1
	v_bfe_u32 v16, v9, 16, 1
	v_add3_u32 v9, v9, v16, s16
	v_add3_u32 v8, v8, v15, s16
	v_add3_u32 v13, v13, v14, s16
	v_add3_u32 v11, v12, v11, s16
	v_lshrrev_b32_e32 v12, 16, v11
	v_lshrrev_b32_e32 v13, 16, v13
	v_lshrrev_b32_e32 v8, 16, v8
	v_lshrrev_b32_e32 v9, 16, v9
	v_and_or_b32 v11, v5, s20, v9
	v_and_or_b32 v10, v10, s20, v8
	v_and_or_b32 v9, v17, s20, v13
	v_and_or_b32 v8, v18, s20, v12
	global_store_dwordx4 v[6:7], v[8:11], off offset:256
	global_load_dwordx4 v[8:11], v[42:43], off offset:768
	s_nop 0
	global_load_dwordx4 v[12:15], v[42:43], off offset:784
	v_lshlrev_b32_e32 v25, 16, v1
	v_lshlrev_b32_e32 v24, 16, v0
	v_and_b32_e32 v1, 0xffff0000, v1
	v_and_b32_e32 v0, 0xffff0000, v0
	v_mul_f32_e32 v28, 0xbfb8aa3b, v0
	v_mul_f32_e32 v30, 0xbfb8aa3b, v1
	v_exp_f32_e32 v28, v28
	v_exp_f32_e32 v30, v30
	v_lshlrev_b32_e32 v26, 16, v2
	v_mul_f32_e32 v5, 0xbfb8aa3b, v24
	v_mul_f32_e32 v31, 0xbfb8aa3b, v26
	v_mul_f32_e32 v29, 0xbfb8aa3b, v25
	v_exp_f32_e32 v5, v5
	v_exp_f32_e32 v86, v31
	v_add_f32_e32 v31, 1.0, v28
	v_add_f32_e32 v87, 1.0, v30
	ds_read_b128 v[16:19], v76 offset:768
	ds_read_b128 v[20:23], v76 offset:784
	v_exp_f32_e32 v29, v29
	v_rcp_f32_e32 v30, v31
	v_rcp_f32_e32 v31, v87
	v_add_f32_e32 v5, 1.0, v5
	v_add_f32_e32 v29, 1.0, v29
	v_rcp_f32_e32 v28, v5
	v_add_f32_e32 v5, 1.0, v86
	v_pk_mul_f32 v[0:1], v[30:31], v[0:1]
	v_rcp_f32_e32 v29, v29
	v_and_b32_e32 v2, 0xffff0000, v2
	v_pk_mul_f32 v[0:1], v[4:5], v[0:1] op_sel_hi:[0,1]
	v_lshlrev_b32_e32 v27, 16, v3
	v_pk_mul_f32 v[24:25], v[28:29], v[24:25]
	v_and_b32_e32 v3, 0xffff0000, v3
	v_pk_mul_f32 v[24:25], v[4:5], v[24:25] op_sel_hi:[0,1]
	s_waitcnt vmcnt(1) lgkmcnt(1)
	v_pk_mul_f32 v[10:11], v[18:19], v[10:11]
	v_pk_mul_f32 v[8:9], v[16:17], v[8:9]
	v_mov_b32_e32 v17, v10
	v_mov_b32_e32 v10, v9
	v_pk_mul_f32 v[0:1], v[0:1], v[10:11]
	v_mul_f32_e32 v10, 0xbfb8aa3b, v2
	v_exp_f32_e32 v11, v10
	s_waitcnt vmcnt(0) lgkmcnt(0)
	v_pk_mul_f32 v[14:15], v[22:23], v[14:15]
	v_pk_mul_f32 v[12:13], v[20:21], v[12:13]
	v_mov_b32_e32 v16, v8
	v_rcp_f32_e32 v10, v5
	v_mul_f32_e32 v5, 0xbfb8aa3b, v27
	v_mov_b32_e32 v8, v12
	v_mov_b32_e32 v9, v14
	v_mov_b32_e32 v14, v13
	v_pk_mul_f32 v[12:13], v[24:25], v[16:17]
	v_exp_f32_e32 v5, v5
	v_add_f32_e32 v16, 1.0, v11
	v_mul_f32_e32 v11, 0xbfb8aa3b, v3
	v_exp_f32_e32 v17, v11
	v_add_f32_e32 v5, 1.0, v5
	v_rcp_f32_e32 v11, v5
	v_rcp_f32_e32 v16, v16
	v_add_f32_e32 v5, 1.0, v17
	v_rcp_f32_e32 v17, v5
	v_pk_mul_f32 v[10:11], v[10:11], v[26:27]
	v_pk_mul_f32 v[2:3], v[16:17], v[2:3]
	s_nop 0
	v_pk_mul_f32 v[2:3], v[4:5], v[2:3] op_sel_hi:[0,1]
	v_pk_mul_f32 v[10:11], v[4:5], v[10:11] op_sel_hi:[0,1]
	v_pk_mul_f32 v[2:3], v[2:3], v[14:15]
	v_pk_mul_f32 v[8:9], v[10:11], v[8:9]
	v_bfe_u32 v4, v3, 16, 1
	v_bfe_u32 v5, v2, 16, 1
	v_bfe_u32 v10, v1, 16, 1
	v_bfe_u32 v11, v0, 16, 1
	v_add3_u32 v0, v0, v11, s16
	v_add3_u32 v1, v1, v10, s16
	v_add3_u32 v2, v2, v5, s16
	v_add3_u32 v3, v3, v4, s16
	v_bfe_u32 v4, v12, 16, 1
	v_bfe_u32 v5, v13, 16, 1
	v_bfe_u32 v10, v8, 16, 1
	v_bfe_u32 v11, v9, 16, 1
	v_add3_u32 v9, v9, v11, s16
	v_add3_u32 v8, v8, v10, s16
	v_add3_u32 v5, v13, v5, s16
	v_add3_u32 v4, v12, v4, s16
	v_lshrrev_b32_e32 v4, 16, v4
	v_lshrrev_b32_e32 v5, 16, v5
	v_lshrrev_b32_e32 v8, 16, v8
	v_lshrrev_b32_e32 v9, 16, v9
	v_and_or_b32 v3, v3, s20, v9
	v_and_or_b32 v2, v2, s20, v8
	v_and_or_b32 v1, v1, s20, v5
	v_and_or_b32 v0, v0, s20, v4
	global_store_dwordx4 v[6:7], v[0:3], off offset:384
	s_barrier
	s_cbranch_scc1 .Lglao_done

.Lglao_done:
	v_readlane_b32 s48, v240, 11
	v_readlane_b32 s49, v240, 12
	v_readlane_b32 s50, v240, 13
	v_readlane_b32 s51, v240, 14
	v_readlane_b32 s52, v240, 15
	v_readlane_b32 s53, v240, 16
	v_readlane_b32 s54, v240, 17
	v_readlane_b32 s55, v240, 18
	s_waitcnt vmcnt(0)
	s_waitcnt lgkmcnt(0)
	s_barrier
	v_readlane_b32 s4, v240, 9
	v_readlane_b32 s5, v240, 10
	v_readlane_b32 s6, v240, 35
	v_readlane_b32 s7, v240, 36
	s_mov_b64 s[8:9], exec
	s_and_b64 exec, exec, s[4:5]
	s_cbranch_execz .Lb224_skip
	buffer_wbl2 sc1
	s_waitcnt vmcnt(0)
	v_mov_b32_e32 v1, 1
	v_mov_b32_e32 v2, 0x300
	s_nop 4
	global_atomic_add v2, v1, s[6:7]
	s_mov_b32 s10, 0
.Lb224_spin:
	global_load_dword v3, v2, s[6:7] sc1
	s_waitcnt vmcnt(0)
	v_cmp_gt_u32_e32 vcc, 0xe0, v3
	s_cbranch_vccz .Lb224_ok
	s_sleep 1
	s_add_u32 s10, s10, 1
	s_cmp_lt_u32 s10, 0x40000
	s_cbranch_scc1 .Lb224_spin
.Lb224_ok:
	buffer_inv sc1
	s_waitcnt vmcnt(0)
.Lb224_skip:
	s_mov_b64 exec, s[8:9]
	s_barrier
	s_sub_i32 s3, s2, 32
	s_lshl_b32 s0, s3, 3
	s_add_i32 s8, s57, s0
	s_waitcnt vmcnt(0)
	v_readlane_b32 s60, v240, 1
	v_readlane_b32 s61, v240, 2
	v_readlane_b32 s62, v240, 3
	v_readlane_b32 s63, v240, 4
	v_readlane_b32 s64, v240, 5
	v_readlane_b32 s65, v240, 6
	v_readlane_b32 s66, v240, 7
	v_readlane_b32 s67, v240, 8
	s_add_i32 s9, s80, 0xffffff00
	s_mul_i32 s4, s57, 0x2100
	v_lshrrev_b32_e32 v55, 3, v146
	v_and_b32_e32 v56, 7, v146
	v_mul_u32_u24_e32 v44, 0x84, v55
	v_lshl_add_u32 v44, v56, 4, v44
	v_add_u32_e32 v44, s4, v44
	v_add_u32_e32 v45, 0x420, v44
	v_add_u32_e32 v46, 0x840, v44
	v_add_u32_e32 v47, 0xc60, v44
	v_add_u32_e32 v48, 0x1080, v44
	v_add_u32_e32 v49, 0x14a0, v44
	v_add_u32_e32 v50, 0x18c0, v44
	v_add_u32_e32 v51, 0x1ce0, v44
	v_mul_u32_u24_e32 v52, 0x420, v56
	v_lshl_add_u32 v52, v55, 2, v52
	v_add_u32_e32 v52, s4, v52
	v_lshrrev_b32_e32 v55, 3, v146
	v_and_b32_e32 v56, 7, v146
	s_mov_b32 s4, 0x5800
	v_mul_lo_u32 v53, v55, s4
	v_lshl_add_u32 v53, v56, 4, v53
	s_mov_b32 s4, 0x1000
	v_mul_lo_u32 v54, v55, s4
	v_lshl_add_u32 v54, v56, 4, v54
	s_mov_b32 s0, s8
	s_cmp_ge_u32 s0, 0x2c00
	s_cbranch_scc1 .Lcv_done_p7up
	s_lshr_b32 s10, s0, 5
	s_mul_i32 s10, s10, 0x1746
	s_lshr_b32 s10, s10, 16
	s_mul_i32 s11, s10, 352
	s_sub_u32 s11, s0, s11
	s_lshl_b32 s5, s11, 5
	s_lshr_b32 s6, s5, 8
	s_lshl_b32 s6, s6, 7
	s_and_b32 s7, s5, 0x7f
	s_add_u32 s6, s6, s7
	s_bitcmp1_b32 s5, 7
	s_mov_b32 s5, s6
	s_cselect_b32 s12, s64, s62
	s_cselect_b32 s13, s65, s63
	s_mul_i32 s6, s10, 0x160000
	s_lshl_b32 s5, s5, 2
	s_add_u32 s6, s6, s5
	s_add_u32 s12, s12, s6
	s_addc_u32 s13, s13, 0
	global_load_dwordx4 v[64:67], v53, s[12:13] nt
	s_add_u32 s12, s12, 0x2c000
	s_addc_u32 s13, s13, 0
	global_load_dwordx4 v[68:71], v53, s[12:13] nt
	s_add_u32 s12, s12, 0x2c000
	s_addc_u32 s13, s13, 0
	global_load_dwordx4 v[72:75], v53, s[12:13] nt
	s_add_u32 s12, s12, 0x2c000
	s_addc_u32 s13, s13, 0
	global_load_dwordx4 v[76:79], v53, s[12:13] nt
	s_add_u32 s12, s12, 0x2c000
	s_addc_u32 s13, s13, 0
	global_load_dwordx4 v[80:83], v53, s[12:13] nt
	s_add_u32 s12, s12, 0x2c000
	s_addc_u32 s13, s13, 0
	global_load_dwordx4 v[84:87], v53, s[12:13] nt
	s_add_u32 s12, s12, 0x2c000
	s_addc_u32 s13, s13, 0
	global_load_dwordx4 v[88:91], v53, s[12:13] nt
	s_add_u32 s12, s12, 0x2c000
	s_addc_u32 s13, s13, 0
	global_load_dwordx4 v[92:95], v53, s[12:13] nt
	s_add_u32 s1, s0, s9
	s_cmp_ge_u32 s1, 0x2c00
	s_cbranch_scc1 .Lcv_only1_p7up
	s_lshr_b32 s10, s1, 5
	s_mul_i32 s10, s10, 0x1746
	s_lshr_b32 s10, s10, 16
	s_mul_i32 s11, s10, 352
	s_sub_u32 s11, s1, s11
	s_lshl_b32 s5, s11, 5
	s_lshr_b32 s6, s5, 8
	s_lshl_b32 s6, s6, 7
	s_and_b32 s7, s5, 0x7f
	s_add_u32 s6, s6, s7
	s_bitcmp1_b32 s5, 7
	s_mov_b32 s5, s6
	s_cselect_b32 s12, s64, s62
	s_cselect_b32 s13, s65, s63
	s_mul_i32 s6, s10, 0x160000
	s_lshl_b32 s5, s5, 2
	s_add_u32 s6, s6, s5
	s_add_u32 s12, s12, s6
	s_addc_u32 s13, s13, 0
	global_load_dwordx4 v[96:99], v53, s[12:13] nt
	s_add_u32 s12, s12, 0x2c000
	s_addc_u32 s13, s13, 0
	global_load_dwordx4 v[100:103], v53, s[12:13] nt
	s_add_u32 s12, s12, 0x2c000
	s_addc_u32 s13, s13, 0
	global_load_dwordx4 v[104:107], v53, s[12:13] nt
	s_add_u32 s12, s12, 0x2c000
	s_addc_u32 s13, s13, 0
	global_load_dwordx4 v[108:111], v53, s[12:13] nt
	s_add_u32 s12, s12, 0x2c000
	s_addc_u32 s13, s13, 0
	global_load_dwordx4 v[112:115], v53, s[12:13] nt
	s_add_u32 s12, s12, 0x2c000
	s_addc_u32 s13, s13, 0
	global_load_dwordx4 v[116:119], v53, s[12:13] nt
	s_add_u32 s12, s12, 0x2c000
	s_addc_u32 s13, s13, 0
	global_load_dwordx4 v[120:123], v53, s[12:13] nt
	s_add_u32 s12, s12, 0x2c000
	s_addc_u32 s13, s13, 0
	global_load_dwordx4 v[124:127], v53, s[12:13] nt
	s_waitcnt vmcnt(8)
	s_branch .Lcv_procA_p7up
